# NA softmax VALU stream reordered so max / add trees are not back-to-back dependent
# baseline (speedup 1.0000x reference)
.Lna_nostag:
	s_add_u32 s11, s52, 1
	s_cmp_lt_u32 s11, s51
	s_cselect_b32 s67, 1, 0
	s_cmp_lt_u32 s52, s50
	s_cbranch_scc0 .Lna_ctx
	s_add_u32 s1, s49, s52
	s_sub_u32 s2, s1, s47
	s_cmp_lt_u32 s2, 8
	s_cselect_b32 s4, 1, 0
	s_sub_u32 s2, s1, s48
	s_cmp_lt_u32 s2, 8
	s_cselect_b32 s5, 1, 0
	s_or_b32 s6, s4, s5
	s_cmp_eq_u32 s6, 0
	s_cbranch_scc1 .Lna_endcompute
	s_sub_u32 s2, s1, s46
	s_add_u32 s2, s2, 7
	s_cmp_eq_u32 s4, 1
	s_cselect_b32 s6, s2, 15
	s_lshl_b32 s6, s6, 7
	s_add_u32 s78, s6, 0x12000
	s_sub_u32 s2, s2, 1
	s_cmp_eq_u32 s5, 1
	s_cselect_b32 s6, s2, 15
	s_lshl_b32 s6, s6, 7
	s_add_u32 s79, s6, 0x12000
	v_add_u32_e32 v232, s66, v198
	v_add_u32_e32 v233, s66, v200
	ds_read_b128 v[112:115], v232 offset:0
	ds_read_b128 v[116:119], v232 offset:4608
	ds_read_b128 v[120:123], v232 offset:64
	ds_read_b128 v[124:127], v232 offset:4672
	ds_read_b128 v[128:131], v232 offset:128
	ds_read_b128 v[132:135], v232 offset:4736
	ds_read_b128 v[136:139], v232 offset:192
	ds_read_b128 v[140:143], v232 offset:4800
	s_waitcnt lgkmcnt(6)
	v_mfma_f32_16x16x32_bf16 v[144:147], v[112:115], v[64:67], 0
	v_mfma_f32_16x16x32_bf16 v[148:151], v[116:119], v[64:67], 0
	v_add_u32_e32 v160, s78, v202
	ds_read_b32 v160, v160
	v_add_u32_e32 v161, s78, v203
	ds_read_b32 v161, v161
	v_add_u32_e32 v162, s78, v204
	ds_read_b32 v162, v162
	v_add_u32_e32 v163, s78, v205
	ds_read_b32 v163, v163
	v_add_u32_e32 v164, s78, v206
	ds_read_b32 v164, v164
	v_add_u32_e32 v165, s78, v207
	ds_read_b32 v165, v165
	v_add_u32_e32 v166, s78, v208
	ds_read_b32 v166, v166
	v_add_u32_e32 v167, s78, v209
	ds_read_b32 v167, v167
	s_waitcnt lgkmcnt(12)
	v_mfma_f32_16x16x32_bf16 v[144:147], v[120:123], v[68:71], v[144:147]
	v_mfma_f32_16x16x32_bf16 v[148:151], v[124:127], v[68:71], v[148:151]
	s_waitcnt lgkmcnt(10)
	v_mfma_f32_16x16x32_bf16 v[144:147], v[128:131], v[72:75], v[144:147]
	v_mfma_f32_16x16x32_bf16 v[148:151], v[132:135], v[72:75], v[148:151]
	s_waitcnt lgkmcnt(8)
	v_mfma_f32_16x16x32_bf16 v[144:147], v[136:139], v[76:79], v[144:147]
	v_mfma_f32_16x16x32_bf16 v[148:151], v[140:143], v[76:79], v[148:151]
	s_waitcnt lgkmcnt(0)
	v_add_u32_e32 v179, s79, v202
	ds_read_b32 v179, v179
	v_add_u32_e32 v180, s79, v203
	ds_read_b32 v180, v180
	v_add_u32_e32 v181, s79, v204
	ds_read_b32 v181, v181
	v_add_u32_e32 v182, s79, v205
	ds_read_b32 v182, v182
	v_add_u32_e32 v183, s79, v206
	ds_read_b32 v183, v183
	v_add_u32_e32 v184, s79, v207
	ds_read_b32 v184, v184
	v_add_u32_e32 v185, s79, v208
	ds_read_b32 v185, v185
	v_add_u32_e32 v186, s79, v209
	ds_read_b32 v186, v186
	v_mfma_f32_16x16x32_bf16 v[152:155], v[112:115], v[80:83], 0
	v_mfma_f32_16x16x32_bf16 v[156:159], v[116:119], v[80:83], 0
	ds_read_b64_tr_b16 v[112:113], v233 offset:0
	ds_read_b64_tr_b16 v[114:115], v233 offset:4608
	ds_read_b64_tr_b16 v[116:117], v233 offset:32
	ds_read_b64_tr_b16 v[118:119], v233 offset:4640
	v_fma_f32 v160, v144, s53, v160
	v_fma_f32 v161, v145, s53, v161
	v_fma_f32 v162, v146, s53, v162
	v_fma_f32 v163, v147, s53, v163
	v_fma_f32 v164, v148, s53, v164
	v_fma_f32 v165, v149, s53, v165
	v_max3_f32 v224, v160, v161, v162
	v_fma_f32 v166, v150, s53, v166
	v_max3_f32 v225, v163, v164, v165
	v_fma_f32 v167, v151, s53, v167
	v_mfma_f32_16x16x32_bf16 v[152:155], v[120:123], v[84:87], v[152:155]
	v_mfma_f32_16x16x32_bf16 v[156:159], v[124:127], v[84:87], v[156:159]
	s_waitcnt lgkmcnt(4)
	ds_read_b64_tr_b16 v[120:121], v233 offset:64
	ds_read_b64_tr_b16 v[122:123], v233 offset:4672
	ds_read_b64_tr_b16 v[124:125], v233 offset:96
	ds_read_b64_tr_b16 v[126:127], v233 offset:4704
	v_max3_f32 v224, v224, v166, v167
	v_max_f32_e32 v224, v224, v225
	v_cmp_gt_f32_e32 vcc, v224, v219
	s_cbranch_vccnz .Lna_rare_L_b0
.Lna_cont_L_b0:
	v_sub_f32_e32 v160, v160, v218
	v_sub_f32_e32 v161, v161, v218
	v_sub_f32_e32 v162, v162, v218
	v_sub_f32_e32 v163, v163, v218
	v_sub_f32_e32 v164, v164, v218
	v_sub_f32_e32 v165, v165, v218
	v_sub_f32_e32 v166, v166, v218
	v_mfma_f32_16x16x32_bf16 v[152:155], v[128:131], v[88:91], v[152:155]
	v_mfma_f32_16x16x32_bf16 v[156:159], v[132:135], v[88:91], v[156:159]
	ds_read_b64_tr_b16 v[128:129], v233 offset:128
	ds_read_b64_tr_b16 v[130:131], v233 offset:4736
	ds_read_b64_tr_b16 v[132:133], v233 offset:160
	ds_read_b64_tr_b16 v[134:135], v233 offset:4768
	v_sub_f32_e32 v167, v167, v218
	v_exp_f32_e32 v160, v160
	v_exp_f32_e32 v161, v161
	v_exp_f32_e32 v162, v162
	v_exp_f32_e32 v163, v163
	v_add_f32_e32 v224, v160, v161
	v_exp_f32_e32 v164, v164
	v_add_f32_e32 v225, v162, v163
	v_exp_f32_e32 v165, v165
	v_exp_f32_e32 v166, v166
	v_mfma_f32_16x16x32_bf16 v[152:155], v[136:139], v[92:95], v[152:155]
	v_mfma_f32_16x16x32_bf16 v[156:159], v[140:143], v[92:95], v[156:159]
	s_waitcnt lgkmcnt(8)
	ds_read_b64_tr_b16 v[136:137], v233 offset:192
	ds_read_b64_tr_b16 v[138:139], v233 offset:4800
	ds_read_b64_tr_b16 v[140:141], v233 offset:224
	ds_read_b64_tr_b16 v[142:143], v233 offset:4832
	v_add_f32_e32 v226, v164, v165
	v_exp_f32_e32 v167, v167
	v_add_f32_e32 v224, v224, v225
	v_add_f32_e32 v227, v166, v167
	v_cvt_pk_bf16_f32 v168, v160, v161
	v_add_f32_e32 v226, v226, v227
	v_cvt_pk_bf16_f32 v169, v162, v163
	v_add_f32_e32 v224, v224, v226
	v_cvt_pk_bf16_f32 v170, v164, v165
	v_add_f32_e32 v220, v220, v224
	v_cvt_pk_bf16_f32 v171, v166, v167
	s_nop 0
	s_waitcnt lgkmcnt(12)
	v_mfma_f32_16x16x32_bf16 v[0:3], v[112:115], v[168:171], v[0:3]
	v_fma_f32 v179, v152, s53, v179
	v_fma_f32 v180, v153, s53, v180
	v_fma_f32 v181, v154, s53, v181
	v_fma_f32 v182, v155, s53, v182
	v_fma_f32 v183, v156, s53, v183
	s_waitcnt lgkmcnt(12)
	v_mfma_f32_16x16x32_bf16 v[4:7], v[116:119], v[168:171], v[4:7]
	v_fma_f32 v184, v157, s53, v184
	v_max3_f32 v228, v179, v180, v181
	v_fma_f32 v185, v158, s53, v185
	v_max3_f32 v229, v182, v183, v184
	v_fma_f32 v186, v159, s53, v186
	s_waitcnt lgkmcnt(10)
	v_mfma_f32_16x16x32_bf16 v[8:11], v[120:123], v[168:171], v[8:11]
	v_max3_f32 v228, v228, v185, v186
	v_max_f32_e32 v228, v228, v229
	v_cmp_gt_f32_e32 vcc, v228, v222
	s_cbranch_vccnz .Lna_rare_L_b1
.Lna_cont_L_b1:
	v_sub_f32_e32 v179, v179, v221
	s_waitcnt lgkmcnt(8)
	v_mfma_f32_16x16x32_bf16 v[12:15], v[124:127], v[168:171], v[12:15]
	v_sub_f32_e32 v180, v180, v221
	v_sub_f32_e32 v181, v181, v221
	v_sub_f32_e32 v182, v182, v221
	v_sub_f32_e32 v183, v183, v221
	v_sub_f32_e32 v184, v184, v221
	v_sub_f32_e32 v185, v185, v221
	s_waitcnt lgkmcnt(6)
	v_mfma_f32_16x16x32_bf16 v[16:19], v[128:131], v[168:171], v[16:19]
	v_sub_f32_e32 v186, v186, v221
	v_exp_f32_e32 v179, v179
	v_exp_f32_e32 v180, v180
	v_exp_f32_e32 v181, v181
	v_exp_f32_e32 v182, v182
	s_waitcnt lgkmcnt(4)
	v_mfma_f32_16x16x32_bf16 v[20:23], v[132:135], v[168:171], v[20:23]
	v_add_f32_e32 v228, v179, v180
	v_exp_f32_e32 v183, v183
	v_add_f32_e32 v229, v181, v182
	v_exp_f32_e32 v184, v184
	v_exp_f32_e32 v185, v185
	s_waitcnt lgkmcnt(2)
	v_mfma_f32_16x16x32_bf16 v[24:27], v[136:139], v[168:171], v[24:27]
	v_add_f32_e32 v230, v183, v184
	v_exp_f32_e32 v186, v186
	v_add_f32_e32 v228, v228, v229
	v_add_f32_e32 v231, v185, v186
	v_cvt_pk_bf16_f32 v188, v179, v180
	s_waitcnt lgkmcnt(0)
	v_mfma_f32_16x16x32_bf16 v[28:31], v[140:143], v[168:171], v[28:31]
	v_add_f32_e32 v230, v230, v231
	v_cvt_pk_bf16_f32 v189, v181, v182
	v_add_f32_e32 v228, v228, v230
	v_cvt_pk_bf16_f32 v190, v183, v184
	v_add_f32_e32 v223, v223, v228
	v_cvt_pk_bf16_f32 v191, v185, v186
	s_nop 1
	v_mfma_f32_16x16x32_bf16 v[32:35], v[112:115], v[188:191], v[32:35]
	v_mfma_f32_16x16x32_bf16 v[36:39], v[116:119], v[188:191], v[36:39]
	v_mfma_f32_16x16x32_bf16 v[40:43], v[120:123], v[188:191], v[40:43]
	v_mfma_f32_16x16x32_bf16 v[44:47], v[124:127], v[188:191], v[44:47]
	v_mfma_f32_16x16x32_bf16 v[48:51], v[128:131], v[188:191], v[48:51]
	v_mfma_f32_16x16x32_bf16 v[52:55], v[132:135], v[188:191], v[52:55]
	v_mfma_f32_16x16x32_bf16 v[56:59], v[136:139], v[188:191], v[56:59]
	v_mfma_f32_16x16x32_bf16 v[60:63], v[140:143], v[188:191], v[60:63]
	s_branch .Lna_endcompute

.Lna_ctx_grp:
	ds_read_b128 v[112:115], v232 offset:0
	ds_read_b128 v[116:119], v232 offset:4608
	ds_read_b128 v[120:123], v232 offset:64
	ds_read_b128 v[124:127], v232 offset:4672
	ds_read_b128 v[128:131], v232 offset:128
	ds_read_b128 v[132:135], v232 offset:4736
	ds_read_b128 v[136:139], v232 offset:192
	ds_read_b128 v[140:143], v232 offset:4800
	s_waitcnt lgkmcnt(6)
	v_mfma_f32_16x16x32_bf16 v[144:147], v[112:115], v[64:67], 0
	v_mfma_f32_16x16x32_bf16 v[148:151], v[116:119], v[64:67], 0
	s_waitcnt lgkmcnt(4)
	v_mfma_f32_16x16x32_bf16 v[144:147], v[120:123], v[68:71], v[144:147]
	v_mfma_f32_16x16x32_bf16 v[148:151], v[124:127], v[68:71], v[148:151]
	s_waitcnt lgkmcnt(2)
	v_mfma_f32_16x16x32_bf16 v[144:147], v[128:131], v[72:75], v[144:147]
	v_mfma_f32_16x16x32_bf16 v[148:151], v[132:135], v[72:75], v[148:151]
	s_waitcnt lgkmcnt(0)
	v_mfma_f32_16x16x32_bf16 v[144:147], v[136:139], v[76:79], v[144:147]
	v_mfma_f32_16x16x32_bf16 v[148:151], v[140:143], v[76:79], v[148:151]
	v_mfma_f32_16x16x32_bf16 v[152:155], v[112:115], v[80:83], 0
	v_mfma_f32_16x16x32_bf16 v[156:159], v[116:119], v[80:83], 0
	ds_read_b64_tr_b16 v[112:113], v233 offset:0
	ds_read_b64_tr_b16 v[114:115], v233 offset:4608
	ds_read_b64_tr_b16 v[116:117], v233 offset:32
	ds_read_b64_tr_b16 v[118:119], v233 offset:4640
	s_nop 0
	v_fma_f32 v160, v144, s53, -v218
	v_fma_f32 v161, v145, s53, -v218
	v_fma_f32 v162, v146, s53, -v218
	v_fma_f32 v163, v147, s53, -v218
	v_fma_f32 v164, v148, s53, -v218
	v_fma_f32 v165, v149, s53, -v218
	v_max3_f32 v224, v160, v161, v162
	v_fma_f32 v166, v150, s53, -v218
	v_mfma_f32_16x16x32_bf16 v[152:155], v[120:123], v[84:87], v[152:155]
	v_mfma_f32_16x16x32_bf16 v[156:159], v[124:127], v[84:87], v[156:159]
	ds_read_b64_tr_b16 v[120:121], v233 offset:64
	ds_read_b64_tr_b16 v[122:123], v233 offset:4672
	ds_read_b64_tr_b16 v[124:125], v233 offset:96
	ds_read_b64_tr_b16 v[126:127], v233 offset:4704
	v_max3_f32 v225, v163, v164, v165
	v_fma_f32 v167, v151, s53, -v218
	v_max3_f32 v224, v224, v166, v167
	v_max_f32_e32 v224, v224, v225
	v_cmp_lt_f32_e32 vcc, 0x41000000, v224
	s_cbranch_vccnz .Lna_rare_C_b0
.Lna_cont_C_b0:
	v_exp_f32_e32 v160, v160
	v_exp_f32_e32 v161, v161
	v_exp_f32_e32 v162, v162
	v_mfma_f32_16x16x32_bf16 v[152:155], v[128:131], v[88:91], v[152:155]
	v_mfma_f32_16x16x32_bf16 v[156:159], v[132:135], v[88:91], v[156:159]
	ds_read_b64_tr_b16 v[128:129], v233 offset:128
	ds_read_b64_tr_b16 v[130:131], v233 offset:4736
	ds_read_b64_tr_b16 v[132:133], v233 offset:160
	ds_read_b64_tr_b16 v[134:135], v233 offset:4768
	v_exp_f32_e32 v163, v163
	v_add_f32_e32 v224, v160, v161
	v_exp_f32_e32 v164, v164
	v_add_f32_e32 v225, v162, v163
	v_exp_f32_e32 v165, v165
	v_exp_f32_e32 v166, v166
	v_add_f32_e32 v226, v164, v165
	v_exp_f32_e32 v167, v167
	v_mfma_f32_16x16x32_bf16 v[152:155], v[136:139], v[92:95], v[152:155]
	v_mfma_f32_16x16x32_bf16 v[156:159], v[140:143], v[92:95], v[156:159]
	s_waitcnt lgkmcnt(8)
	ds_read_b64_tr_b16 v[136:137], v233 offset:192
	ds_read_b64_tr_b16 v[138:139], v233 offset:4800
	ds_read_b64_tr_b16 v[140:141], v233 offset:224
	ds_read_b64_tr_b16 v[142:143], v233 offset:4832
	v_add_f32_e32 v224, v224, v225
	v_add_f32_e32 v227, v166, v167
	v_cvt_pk_bf16_f32 v168, v160, v161
	v_add_f32_e32 v226, v226, v227
	v_cvt_pk_bf16_f32 v169, v162, v163
	v_add_f32_e32 v224, v224, v226
	v_cvt_pk_bf16_f32 v170, v164, v165
	v_add_f32_e32 v220, v220, v224
	v_cvt_pk_bf16_f32 v171, v166, v167
	s_nop 0
	s_waitcnt lgkmcnt(12)
	v_mfma_f32_16x16x32_bf16 v[0:3], v[112:115], v[168:171], v[0:3]
	v_fma_f32 v179, v152, s53, -v221
	v_fma_f32 v180, v153, s53, -v221
	v_fma_f32 v181, v154, s53, -v221
	v_fma_f32 v182, v155, s53, -v221
	s_waitcnt lgkmcnt(12)
	v_mfma_f32_16x16x32_bf16 v[4:7], v[116:119], v[168:171], v[4:7]
	v_fma_f32 v183, v156, s53, -v221
	v_fma_f32 v184, v157, s53, -v221
	v_max3_f32 v228, v179, v180, v181
	v_fma_f32 v185, v158, s53, -v221
	s_waitcnt lgkmcnt(10)
	v_mfma_f32_16x16x32_bf16 v[8:11], v[120:123], v[168:171], v[8:11]
	v_max3_f32 v229, v182, v183, v184
	v_fma_f32 v186, v159, s53, -v221
	v_max3_f32 v228, v228, v185, v186
	v_max_f32_e32 v228, v228, v229
	s_waitcnt lgkmcnt(8)
	v_mfma_f32_16x16x32_bf16 v[12:15], v[124:127], v[168:171], v[12:15]
	v_cmp_lt_f32_e32 vcc, 0x41000000, v228
	s_cbranch_vccnz .Lna_rare_C_b1
.Lna_cont_C_b1:
	v_exp_f32_e32 v179, v179
	v_exp_f32_e32 v180, v180
	v_exp_f32_e32 v181, v181
	s_waitcnt lgkmcnt(6)
	v_mfma_f32_16x16x32_bf16 v[16:19], v[128:131], v[168:171], v[16:19]
	v_exp_f32_e32 v182, v182
	v_add_f32_e32 v228, v179, v180
	v_exp_f32_e32 v183, v183
	v_add_f32_e32 v229, v181, v182
	s_waitcnt lgkmcnt(4)
	v_mfma_f32_16x16x32_bf16 v[20:23], v[132:135], v[168:171], v[20:23]
	v_exp_f32_e32 v184, v184
	v_exp_f32_e32 v185, v185
	v_add_f32_e32 v230, v183, v184
	v_exp_f32_e32 v186, v186
	s_waitcnt lgkmcnt(2)
	v_mfma_f32_16x16x32_bf16 v[24:27], v[136:139], v[168:171], v[24:27]
	v_add_f32_e32 v228, v228, v229
	v_add_f32_e32 v231, v185, v186
	v_cvt_pk_bf16_f32 v188, v179, v180
	v_add_f32_e32 v230, v230, v231
	s_waitcnt lgkmcnt(0)
	v_mfma_f32_16x16x32_bf16 v[28:31], v[140:143], v[168:171], v[28:31]
	v_cvt_pk_bf16_f32 v189, v181, v182
	v_add_f32_e32 v228, v228, v230
	v_cvt_pk_bf16_f32 v190, v183, v184
	v_add_f32_e32 v223, v223, v228
	v_cvt_pk_bf16_f32 v191, v185, v186
	s_nop 1
	v_mfma_f32_16x16x32_bf16 v[32:35], v[112:115], v[188:191], v[32:35]
	v_mfma_f32_16x16x32_bf16 v[36:39], v[116:119], v[188:191], v[36:39]
	v_mfma_f32_16x16x32_bf16 v[40:43], v[120:123], v[188:191], v[40:43]
	v_mfma_f32_16x16x32_bf16 v[44:47], v[124:127], v[188:191], v[44:47]
	v_mfma_f32_16x16x32_bf16 v[48:51], v[128:131], v[188:191], v[48:51]
	v_mfma_f32_16x16x32_bf16 v[52:55], v[132:135], v[188:191], v[52:55]
	v_mfma_f32_16x16x32_bf16 v[56:59], v[136:139], v[188:191], v[56:59]
	v_mfma_f32_16x16x32_bf16 v[60:63], v[140:143], v[188:191], v[60:63]
	v_add_u32_e32 v232, 0x2400, v232
	v_add_u32_e32 v233, 0x2400, v233
	s_add_u32 s90, s90, 1
	s_cmp_lt_u32 s90, 2
	s_cbranch_scc1 .Lna_ctx_grp
